# v60 + waves 4..7 start the weight transposes ~1.7 us late so read and write phases interleave
# baseline (speedup 1.0000x reference)
.LBB0_8:
	s_or_b64 exec, exec, s[4:5]
	s_load_dwordx16 s[12:27], s[0:1], 0x0
	s_load_dwordx16 s[36:51], s[0:1], 0x40
	s_load_dwordx16 s[52:67], s[0:1], 0x80
	v_readlane_b32 s0, v255, 0
	v_ashrrev_i32_e32 v2, 6, v1
	s_lshl_b32 s0, s0, 3
	v_writelane_b32 v255, s0, 6
	v_add_u32_e32 v66, s0, v2
	s_movk_i32 s0, 0x1040
	v_and_b32_e32 v69, 63, v1
	v_cmp_gt_i32_e32 vcc, s0, v66
	s_and_saveexec_b64 s[0:1], vcc
	s_cbranch_execz .LBB0_51
	v_readfirstlane_b32 s98, v204
	s_nop 0
	s_bitcmp1_b32 s98, 8
	s_cbranch_scc0 .Ltr_nostag
	s_sleep 60
.Ltr_nostag:
	v_lshlrev_b32_e32 v3, 3, v1
	s_movk_i32 s2, 0x4100
	v_and_b32_e32 v4, 56, v3
	v_lshrrev_b32_e32 v67, 3, v69
	v_mul_lo_u32 v3, v2, s2
	v_add_u32_e32 v3, 16, v3
	v_lshlrev_b32_e32 v5, 2, v1
	v_lshlrev_b32_e32 v7, 2, v67
	v_mul_u32_u24_e32 v8, 0x104, v4
	v_lshrrev_b32_e32 v68, 4, v69
	v_and_b32_e32 v6, 60, v5
	v_add3_u32 v83, v3, v7, v8
	v_mov_b32_e32 v7, 0xff000000
	v_readlane_b32 s2, v255, 4
	v_lshl_add_u32 v5, v6, 2, v3
	v_mul_u32_u24_e32 v3, 0x104, v68
	v_lshl_add_u32 v121, v66, 12, v7
	v_lshl_add_u32 v122, v2, 6, s2
	v_lshlrev_b32_e32 v7, 5, v2
	v_readlane_b32 s2, v255, 0
	v_lshlrev_b32_e32 v2, 1, v2
	s_mov_b32 s8, 0xfff80000
	s_movk_i32 s10, 0xf000
	v_mov_b32_e32 v71, 0
	s_lshl_b32 s33, s94, 3
	v_or_b32_e32 v81, 56, v67
	v_or_b32_e32 v87, 4, v68
	v_or_b32_e32 v89, 8, v68
	v_or_b32_e32 v91, 12, v68
	v_or_b32_e32 v93, 16, v68
	v_or_b32_e32 v95, 20, v68
	v_or_b32_e32 v97, 24, v68
	v_or_b32_e32 v99, 28, v68
	v_or_b32_e32 v101, 32, v68
	v_or_b32_e32 v103, 36, v68
	v_or_b32_e32 v105, 40, v68
	v_or_b32_e32 v107, 44, v68
	v_or_b32_e32 v109, 48, v68
	v_or_b32_e32 v111, 52, v68
	v_or_b32_e32 v113, 56, v68
	v_or_b32_e32 v114, 60, v68
	v_or_b32_e32 v115, 8, v67
	v_or_b32_e32 v116, 16, v67
	v_or_b32_e32 v117, 24, v67
	v_or_b32_e32 v118, 32, v67
	v_or_b32_e32 v119, 40, v67
	v_or_b32_e32 v120, 48, v67
	s_lshl_b32 s34, s94, 15
	s_lshl_b32 s35, s94, 9
	v_lshl_add_u32 v123, s2, 8, v7
	s_lshl_b32 s84, s94, 8
	v_lshl_add_u32 v124, s2, 4, v2
	s_lshl_b32 s85, s94, 4
	s_mov_b64 s[4:5], 0
	s_movk_i32 s86, 0xbff
	s_movk_i32 s87, 0xfff
	s_mov_b32 s9, -1
	s_mov_b32 s11, -1
	v_lshlrev_b32_e32 v70, 2, v6
	v_add_u32_e32 v125, v5, v3
	v_lshlrev_b32_e32 v72, 1, v4
	s_movk_i32 s88, 0x103f
	v_mov_b32_e32 v126, v66
	s_branch .LBB0_11
